# RMSNorm row loops (phases 0, 7, 10): the 8 loop-invariant gain vectors loaded once before the row loop instead of load-wait-scale-store eight times per row
# speedup vs baseline: 1.0065x; 1.0065x over previous
; __device__ __forceinline__ void rms_row_bf16(const float* xrow, const float* gain, bf16_t* orow, int lane) {
;     const f32x4* xr = (const f32x4*)xrow + lane; const f32x4* gr = (const f32x4*)gain + lane;
;     f32x4 v[8]; float s = 0.f;
; #pragma unroll
;     for (int j = 0; j < 8; ++j) { v[j] = __builtin_nontemporal_load(xr + 64 * j); s += (v[j].x * v[j].x + v[j].y * v[j].y) + (v[j].z * v[j].z + v[j].w * v[j].w); }
;     const float rs = rsqrtf(wave_sum(s) * (1.f / D) + EPS);
; __device__ __forceinline__ void phase0(const Frame& F, const Args& a) {
;     ...
;     for (int m = gw; m < M; m += NGW) rms_row_bf16(a.x + (size_t)m * D, a.norm_mix, (bf16_t*)(ws + WS_H) + (size_t)m * D, F.lane);
.LBB0_37:
	s_cmpk_gt_i32 s92, 0x3fff
	v_mov_b32_e32 v3, 0
	s_cbranch_scc1 .LBB0_40
	v_mbcnt_lo_u32_b32 v1, -1, 0
	v_mbcnt_hi_u32_b32 v4, -1, v1
	v_and_b32_e32 v1, 64, v4
	v_add_u32_e32 v5, 64, v1
	v_xor_b32_e32 v1, 1, v4
	v_cmp_lt_i32_e32 vcc, v1, v5
	v_xor_b32_e32 v6, 2, v4
	v_readlane_b32 s36, v242, 1
	v_cndmask_b32_e32 v1, v4, v1, vcc
	v_cmp_lt_i32_e32 vcc, v6, v5
	v_lshlrev_b32_e32 v2, 4, v192
	v_readlane_b32 s42, v242, 7
	v_cndmask_b32_e32 v6, v4, v6, vcc
	v_lshlrev_b32_e32 v40, 2, v6
	v_xor_b32_e32 v6, 4, v4
	v_cmp_lt_i32_e32 vcc, v6, v5
	v_readlane_b32 s43, v242, 8
	s_mov_b64 s[2:3], 0x1400
	v_cndmask_b32_e32 v6, v4, v6, vcc
	v_lshlrev_b32_e32 v41, 2, v6
	v_xor_b32_e32 v6, 8, v4
	v_cmp_lt_i32_e32 vcc, v6, v5
	v_lshl_add_u64 v[26:27], s[42:43], 0, v[2:3]
	v_lshl_add_u64 v[30:31], v[26:27], 0, s[2:3]
	v_cndmask_b32_e32 v6, v4, v6, vcc
	v_lshlrev_b32_e32 v42, 2, v6
	v_xor_b32_e32 v6, 16, v4
	s_mov_b64 s[2:3], 0x1800
	v_cmp_lt_i32_e32 vcc, v6, v5
	v_lshl_add_u64 v[32:33], v[26:27], 0, s[2:3]
	s_mov_b64 s[2:3], 0x1c00
	v_cndmask_b32_e32 v6, v4, v6, vcc
	v_lshl_add_u64 v[34:35], v[26:27], 0, s[2:3]
	v_lshlrev_b32_e32 v43, 2, v6
	v_xor_b32_e32 v6, 32, v4
	s_lshl_b64 s[2:3], s[92:93], 13
	v_readlane_b32 s37, v242, 2
	v_cmp_lt_i32_e32 vcc, v6, v5
	s_add_u32 s2, s36, s2
	s_addc_u32 s3, s37, s3
	v_cndmask_b32_e32 v4, v4, v6, vcc
	s_mov_b64 s[0:1], 0x1000
	v_lshlrev_b32_e32 v44, 2, v4
	v_lshl_add_u64 v[4:5], s[2:3], 0, v[2:3]
	s_ashr_i32 s95, s94, 31
	v_lshl_add_u64 v[28:29], v[26:27], 0, s[0:1]
	v_lshl_add_u64 v[36:37], v[4:5], 0, s[0:1]
	s_lshl_b64 s[0:1], s[94:95], 13
	s_lshl_b64 s[2:3], s[92:93], 12
	s_add_u32 s2, s22, s2
	v_lshlrev_b32_e32 v2, 3, v192
	s_addc_u32 s3, s23, s3
	v_lshl_add_u64 v[2:3], s[2:3], 0, v[2:3]
	s_mov_b64 s[2:3], 0xa400000
	v_lshlrev_b32_e32 v1, 2, v1
	v_lshl_add_u64 v[38:39], v[2:3], 0, s[2:3]
	s_lshl_b64 s[2:3], s[94:95], 12
	v_mov_b32_e32 v45, 0x358637bd
	s_mov_b32 s8, 0x800000
	s_mov_b32 s9, s92
	v_readlane_b32 s38, v242, 3
	v_readlane_b32 s39, v242, 4
	v_readlane_b32 s40, v242, 5
	v_readlane_b32 s41, v242, 6
	v_readlane_b32 s44, v242, 9
	v_readlane_b32 s45, v242, 10
	v_readlane_b32 s46, v242, 11
	v_readlane_b32 s47, v242, 12
	v_readlane_b32 s48, v242, 13
	v_readlane_b32 s49, v242, 14
	v_readlane_b32 s50, v242, 15
	v_readlane_b32 s51, v242, 16
	global_load_dwordx4 v[92:95], v[26:27], off
	global_load_dwordx4 v[96:99], v[26:27], off offset:1024
	global_load_dwordx4 v[100:103], v[26:27], off offset:2048
	global_load_dwordx4 v[104:107], v[26:27], off offset:3072
	global_load_dwordx4 v[108:111], v[28:29], off
	global_load_dwordx4 v[112:115], v[30:31], off
	global_load_dwordx4 v[116:119], v[32:33], off
	global_load_dwordx4 v[120:123], v[34:35], off
	s_waitcnt vmcnt(0)
.LBB0_39:
	global_load_dwordx4 v[46:49], v[36:37], off offset:-4096 nt
	global_load_dwordx4 v[14:17], v[36:37], off offset:-3072 nt
	global_load_dwordx4 v[18:21], v[36:37], off offset:-2048 nt
	global_load_dwordx4 v[10:13], v[36:37], off offset:1024 nt
	global_load_dwordx4 v[22:25], v[36:37], off nt
	global_load_dwordx4 v[50:53], v[36:37], off offset:-1024 nt
	global_load_dwordx4 v[2:5], v[36:37], off offset:3072 nt
	global_load_dwordx4 v[6:9], v[36:37], off offset:2048 nt
	v_mov_b32_e32 v54, v92
	v_mov_b32_e32 v55, v93
	v_mov_b32_e32 v56, v94
	v_mov_b32_e32 v57, v95
	s_add_i32 s9, s9, s94
	v_lshl_add_u64 v[36:37], v[36:37], 0, s[0:1]
	s_cmpk_gt_i32 s9, 0x3fff
	s_waitcnt vmcnt(7)
	v_mov_b32_e32 v60, v47
	s_waitcnt vmcnt(6)
	v_mov_b32_e32 v61, v15
	s_waitcnt vmcnt(5)
	v_pk_mul_f32 v[62:63], v[20:21], v[20:21]
	v_pk_mul_f32 v[64:65], v[18:19], v[18:19]
	s_waitcnt vmcnt(4)
	v_pk_mul_f32 v[66:67], v[12:13], v[12:13]
	v_pk_mul_f32 v[68:69], v[10:11], v[10:11]
	v_mov_b32_e32 v72, v49
	v_mov_b32_e32 v73, v17
	v_mov_b32_e32 v58, v46
	v_mov_b32_e32 v59, v14
	v_mov_b32_e32 v70, v48
	v_mov_b32_e32 v71, v16
	v_pk_mov_b32 v[82:83], v[64:65], v[62:63] op_sel:[1,0]
	v_mov_b32_e32 v65, v63
	v_pk_mov_b32 v[62:63], v[68:69], v[66:67] op_sel:[1,0]
	v_mov_b32_e32 v69, v67
	v_pk_mul_f32 v[60:61], v[60:61], v[60:61]
	v_pk_mul_f32 v[66:67], v[72:73], v[72:73]
	v_pk_fma_f32 v[58:59], v[58:59], v[58:59], v[60:61]
	v_pk_fma_f32 v[60:61], v[70:71], v[70:71], v[66:67]
	s_waitcnt vmcnt(2)
	v_mul_f32_e32 v74, v51, v51
	v_mul_f32_e32 v76, v53, v53
	v_pk_add_f32 v[64:65], v[82:83], v[64:65]
	v_pk_add_f32 v[58:59], v[58:59], v[60:61]
	v_mul_f32_e32 v81, v24, v24
	v_mul_f32_e32 v84, v25, v25
	v_mul_f32_e32 v87, v23, v23
	v_mul_f32_e32 v89, v22, v22
	v_pk_fma_f32 v[72:73], v[50:51], v[50:51], v[74:75] op_sel_hi:[1,1,0]
	v_pk_fma_f32 v[74:75], v[52:53], v[52:53], v[76:77] op_sel_hi:[1,1,0]
	v_pk_add_f32 v[64:65], v[64:65], v[64:65] op_sel:[0,1] op_sel_hi:[1,0]
	v_pk_add_f32 v[58:59], v[58:59], v[58:59] op_sel:[0,1] op_sel_hi:[1,0]
	v_mov_b32_e32 v73, v81
	v_mov_b32_e32 v75, v84
	v_mov_b32_e32 v65, v87
	v_mov_b32_e32 v59, v89
	v_pk_add_f32 v[60:61], v[72:73], v[74:75]
	v_pk_add_f32 v[58:59], v[58:59], v[64:65]
	s_waitcnt vmcnt(0)
	v_mul_f32_e32 v78, v7, v7
	v_mul_f32_e32 v80, v9, v9
	v_pk_add_f32 v[62:63], v[62:63], v[68:69]
	v_pk_add_f32 v[58:59], v[58:59], v[60:61]
	v_mul_f32_e32 v85, v4, v4
	v_mul_f32_e32 v86, v5, v5
	v_mul_f32_e32 v88, v3, v3
	v_mul_f32_e32 v90, v2, v2
	v_pk_fma_f32 v[76:77], v[6:7], v[6:7], v[78:79] op_sel_hi:[1,1,0]
	v_pk_fma_f32 v[78:79], v[8:9], v[8:9], v[80:81] op_sel_hi:[1,1,0]
	v_pk_add_f32 v[62:63], v[62:63], v[62:63] op_sel:[0,1] op_sel_hi:[1,0]
	v_pk_add_f32 v[58:59], v[58:59], v[58:59] op_sel:[0,1] op_sel_hi:[1,0]
	v_mov_b32_e32 v77, v85
	v_mov_b32_e32 v79, v86
	v_mov_b32_e32 v63, v88
	v_mov_b32_e32 v59, v90
	v_pk_add_f32 v[66:67], v[76:77], v[78:79]
	v_pk_add_f32 v[58:59], v[58:59], v[62:63]
	s_nop 0
	v_pk_add_f32 v[58:59], v[58:59], v[66:67]
	s_nop 0
	v_add_f32_e32 v58, v58, v59
	ds_bpermute_b32 v59, v1, v58
	s_waitcnt lgkmcnt(0)
; __device__ __forceinline__ unsigned cvt_pk_bf16(float lo, float hi) { unsigned r; asm volatile("v_cvt_pk_bf16_f32 %0, %1, %2" : "=v"(r) : "v"(lo), "v"(hi)); return r; }
; __device__ __forceinline__ void rms_row_bf16(const float* xrow, const float* gain, bf16_t* orow, int lane) {
;     ...
;     const float rs = rsqrtf(wave_sum(s) * (1.f / D) + EPS);
;     u32x2* o8 = (u32x2*)orow + lane;
; #pragma unroll
;     for (int j = 0; j < 8; ++j) { const f32x4 g = gr[64 * j]; u32x2 w; w.x = cvt_pk_bf16(v[j].x * rs * g.x, v[j].y * rs * g.y); w.y = cvt_pk_bf16(v[j].z * rs * g.z, v[j].w * rs * g.w); o8[64 * j] = w; }
; }
; __device__ __forceinline__ void phase0(const Frame& F, const Args& a) {
;     ...
;     for (int m = gw; m < BATCH * NMEM; m += NGW) rms_row_bf16(a.mem + (size_t)m * D, a.norm_mem, (bf16_t*)(ws + WS_MEMN) + (size_t)m * D, F.lane);
	v_add_f32_e32 v58, v58, v59
	ds_bpermute_b32 v59, v40, v58
	s_waitcnt lgkmcnt(0)
	v_add_f32_e32 v58, v58, v59
	ds_bpermute_b32 v59, v41, v58
	s_waitcnt lgkmcnt(0)
	v_add_f32_e32 v58, v58, v59
	ds_bpermute_b32 v59, v42, v58
	s_waitcnt lgkmcnt(0)
	v_add_f32_e32 v58, v58, v59
	ds_bpermute_b32 v59, v43, v58
	s_waitcnt lgkmcnt(0)
	v_add_f32_e32 v58, v58, v59
	ds_bpermute_b32 v59, v44, v58
	s_waitcnt lgkmcnt(0)
	v_add_f32_e32 v58, v58, v59
	v_fmamk_f32 v58, v58, 0x3a000000, v45
	v_mul_f32_e32 v59, 0x4b800000, v58
	v_cmp_gt_f32_e32 vcc, s8, v58
	s_nop 1
	v_cndmask_b32_e32 v58, v58, v59, vcc
	v_rsq_f32_e32 v58, v58
	s_nop 0
	v_mul_f32_e32 v59, 0x45800000, v58
	v_cndmask_b32_e32 v58, v58, v59, vcc
	v_mul_f32_e32 v46, v46, v58
	v_mul_f32_e32 v47, v47, v58
	v_mul_f32_e32 v48, v48, v58
	v_mul_f32_e32 v49, v49, v58
	s_waitcnt vmcnt(0)
	v_mul_f32_e32 v46, v54, v46
	v_mul_f32_e32 v47, v55, v47
	v_mul_f32_e32 v48, v56, v48
	v_mul_f32_e32 v49, v57, v49
	v_cvt_pk_bf16_f32 v46, v46, v47
	v_cvt_pk_bf16_f32 v47, v48, v49
	global_store_dwordx2 v[38:39], v[46:47], off
	v_mov_b32_e32 v46, v96
	v_mov_b32_e32 v47, v97
	v_mov_b32_e32 v48, v98
	v_mov_b32_e32 v49, v99
	v_mul_f32_e32 v14, v14, v58
	v_mul_f32_e32 v15, v15, v58
	v_mul_f32_e32 v16, v16, v58
	v_mul_f32_e32 v17, v17, v58
	v_mul_f32_e32 v18, v18, v58
	v_mul_f32_e32 v19, v19, v58
	v_mul_f32_e32 v20, v20, v58
	v_mul_f32_e32 v21, v21, v58
	v_mul_f32_e32 v10, v10, v58
	v_mul_f32_e32 v11, v11, v58
	v_mul_f32_e32 v12, v12, v58
	v_mul_f32_e32 v13, v13, v58
	v_mul_f32_e32 v6, v6, v58
	v_mul_f32_e32 v7, v7, v58
	v_mul_f32_e32 v8, v8, v58
	v_mul_f32_e32 v9, v9, v58
	v_mul_f32_e32 v2, v2, v58
	v_mul_f32_e32 v3, v3, v58
	v_mul_f32_e32 v4, v4, v58
	v_mul_f32_e32 v5, v5, v58
	v_mul_f32_e32 v14, v46, v14
	v_mul_f32_e32 v15, v47, v15
	v_mul_f32_e32 v16, v48, v16
	v_mul_f32_e32 v17, v49, v17
	v_cvt_pk_bf16_f32 v14, v14, v15
	v_cvt_pk_bf16_f32 v15, v16, v17
	global_store_dwordx2 v[38:39], v[14:15], off offset:512
	v_mov_b32_e32 v14, v100
	v_mov_b32_e32 v15, v101
	v_mov_b32_e32 v16, v102
	v_mov_b32_e32 v17, v103
	v_mul_f32_e32 v14, v14, v18
	v_mul_f32_e32 v15, v15, v19
	v_mul_f32_e32 v16, v16, v20
	v_mul_f32_e32 v17, v17, v21
	v_cvt_pk_bf16_f32 v14, v14, v15
	v_cvt_pk_bf16_f32 v15, v16, v17
	global_store_dwordx2 v[38:39], v[14:15], off offset:1024
	v_mov_b32_e32 v14, v104
	v_mov_b32_e32 v15, v105
	v_mov_b32_e32 v16, v106
	v_mov_b32_e32 v17, v107
	v_mul_f32_e32 v18, v50, v58
	v_mul_f32_e32 v19, v51, v58
	v_mul_f32_e32 v20, v52, v58
	v_mul_f32_e32 v21, v53, v58
	v_mul_f32_e32 v14, v18, v14
	v_mul_f32_e32 v15, v19, v15
	v_mul_f32_e32 v16, v20, v16
	v_mul_f32_e32 v17, v21, v17
	v_cvt_pk_bf16_f32 v14, v14, v15
	v_cvt_pk_bf16_f32 v15, v16, v17
	global_store_dwordx2 v[38:39], v[14:15], off offset:1536
	v_mov_b32_e32 v14, v108
	v_mov_b32_e32 v15, v109
	v_mov_b32_e32 v16, v110
	v_mov_b32_e32 v17, v111
	v_mul_f32_e32 v18, v22, v58
	v_mul_f32_e32 v19, v23, v58
	v_mul_f32_e32 v20, v24, v58
	v_mul_f32_e32 v21, v25, v58
	v_mul_f32_e32 v14, v18, v14
	v_mul_f32_e32 v15, v19, v15
	v_mul_f32_e32 v16, v20, v16
	v_mul_f32_e32 v17, v21, v17
	v_cvt_pk_bf16_f32 v14, v14, v15
	v_cvt_pk_bf16_f32 v15, v16, v17
	global_store_dwordx2 v[38:39], v[14:15], off offset:2048
	v_mov_b32_e32 v14, v112
	v_mov_b32_e32 v15, v113
	v_mov_b32_e32 v16, v114
	v_mov_b32_e32 v17, v115
	v_mul_f32_e32 v10, v10, v14
	v_mul_f32_e32 v11, v11, v15
	v_mul_f32_e32 v12, v12, v16
	v_mul_f32_e32 v13, v13, v17
	v_cvt_pk_bf16_f32 v10, v10, v11
	v_cvt_pk_bf16_f32 v11, v12, v13
	global_store_dwordx2 v[38:39], v[10:11], off offset:2560
	v_mov_b32_e32 v10, v116
	v_mov_b32_e32 v11, v117
	v_mov_b32_e32 v12, v118
	v_mov_b32_e32 v13, v119
	v_mul_f32_e32 v6, v6, v10
	v_mul_f32_e32 v7, v7, v11
	v_mul_f32_e32 v8, v8, v12
	v_mul_f32_e32 v9, v9, v13
	v_cvt_pk_bf16_f32 v6, v6, v7
	v_cvt_pk_bf16_f32 v7, v8, v9
	global_store_dwordx2 v[38:39], v[6:7], off offset:3072
	v_mov_b32_e32 v6, v120
	v_mov_b32_e32 v7, v121
	v_mov_b32_e32 v8, v122
	v_mov_b32_e32 v9, v123
	v_mul_f32_e32 v2, v2, v6
	v_mul_f32_e32 v3, v3, v7
	v_mul_f32_e32 v4, v4, v8
	v_mul_f32_e32 v5, v5, v9
	v_cvt_pk_bf16_f32 v2, v2, v3
	v_cvt_pk_bf16_f32 v3, v4, v5
	global_store_dwordx2 v[38:39], v[2:3], off offset:3584
	v_lshl_add_u64 v[38:39], v[38:39], 0, s[2:3]
	s_cbranch_scc0 .LBB0_39
.LBB0_40:
	s_cmpk_gt_i32 s92, 0x3ff
	s_cbranch_scc1 .LBB0_43
	v_mbcnt_lo_u32_b32 v1, -1, 0
	v_mbcnt_hi_u32_b32 v4, -1, v1
	v_and_b32_e32 v1, 64, v4
	v_add_u32_e32 v5, 64, v1
	v_xor_b32_e32 v1, 1, v4
	v_cmp_lt_i32_e32 vcc, v1, v5
	v_xor_b32_e32 v6, 2, v4
	v_readlane_b32 s36, v242, 1
	v_cndmask_b32_e32 v1, v4, v1, vcc
	v_cmp_lt_i32_e32 vcc, v6, v5
	v_lshlrev_b32_e32 v2, 4, v192
	v_mov_b32_e32 v3, 0
	v_cndmask_b32_e32 v6, v4, v6, vcc
	v_lshlrev_b32_e32 v28, 2, v6
	v_xor_b32_e32 v6, 4, v4
	v_cmp_lt_i32_e32 vcc, v6, v5
	v_readlane_b32 s44, v242, 9
	v_readlane_b32 s45, v242, 10
	v_cndmask_b32_e32 v6, v4, v6, vcc
	v_lshlrev_b32_e32 v29, 2, v6
	v_xor_b32_e32 v6, 8, v4
	v_cmp_lt_i32_e32 vcc, v6, v5
	v_lshl_add_u64 v[14:15], s[44:45], 0, v[2:3]
	s_mov_b64 s[2:3], 0x1400
	v_cndmask_b32_e32 v6, v4, v6, vcc
	v_lshlrev_b32_e32 v30, 2, v6
	v_xor_b32_e32 v6, 16, v4
	v_lshl_add_u64 v[18:19], v[14:15], 0, s[2:3]
	s_mov_b64 s[2:3], 0x1800
	v_cmp_lt_i32_e32 vcc, v6, v5
	v_lshl_add_u64 v[20:21], v[14:15], 0, s[2:3]
	s_mov_b64 s[2:3], 0x1c00
	v_cndmask_b32_e32 v6, v4, v6, vcc
	v_readlane_b32 s38, v242, 3
	v_lshl_add_u64 v[22:23], v[14:15], 0, s[2:3]
	v_lshlrev_b32_e32 v31, 2, v6
	v_xor_b32_e32 v6, 32, v4
	s_lshl_b64 s[2:3], s[92:93], 13
	v_readlane_b32 s39, v242, 4
	v_cmp_lt_i32_e32 vcc, v6, v5
	s_add_u32 s2, s38, s2
	s_addc_u32 s3, s39, s3
	v_cndmask_b32_e32 v4, v4, v6, vcc
	s_mov_b64 s[0:1], 0x1000
	v_lshlrev_b32_e32 v32, 2, v4
	v_lshl_add_u64 v[4:5], s[2:3], 0, v[2:3]
	s_ashr_i32 s95, s94, 31
	v_lshl_add_u64 v[16:17], v[14:15], 0, s[0:1]
	v_lshl_add_u64 v[24:25], v[4:5], 0, s[0:1]
	s_lshl_b64 s[0:1], s[94:95], 13
	s_lshl_b64 s[2:3], s[92:93], 12
	s_add_u32 s2, s22, s2
	v_lshlrev_b32_e32 v2, 3, v192
	s_addc_u32 s3, s23, s3
	v_lshl_add_u64 v[2:3], s[2:3], 0, v[2:3]
	s_mov_b64 s[2:3], 0x600000
	v_lshlrev_b32_e32 v1, 2, v1
	v_lshl_add_u64 v[26:27], v[2:3], 0, s[2:3]
	s_lshl_b64 s[2:3], s[94:95], 12
	v_mov_b32_e32 v33, 0x358637bd
	s_mov_b32 s8, 0x800000
	s_mov_b32 s9, s92
	v_readlane_b32 s37, v242, 2
	v_readlane_b32 s40, v242, 5
	v_readlane_b32 s41, v242, 6
	v_readlane_b32 s42, v242, 7
	v_readlane_b32 s43, v242, 8
	v_readlane_b32 s46, v242, 11
	v_readlane_b32 s47, v242, 12
	v_readlane_b32 s48, v242, 13
	v_readlane_b32 s49, v242, 14
	v_readlane_b32 s50, v242, 15
	v_readlane_b32 s51, v242, 16
	global_load_dwordx4 v[92:95], v[14:15], off
	global_load_dwordx4 v[96:99], v[14:15], off offset:1024
	global_load_dwordx4 v[100:103], v[14:15], off offset:2048
	global_load_dwordx4 v[104:107], v[14:15], off offset:3072
	global_load_dwordx4 v[108:111], v[16:17], off
	global_load_dwordx4 v[112:115], v[18:19], off
	global_load_dwordx4 v[116:119], v[20:21], off
	global_load_dwordx4 v[120:123], v[22:23], off
	s_waitcnt vmcnt(0)
; __device__ __forceinline__ void rms_row_bf16(const float* xrow, const float* gain, bf16_t* orow, int lane) {
;     const f32x4* xr = (const f32x4*)xrow + lane; const f32x4* gr = (const f32x4*)gain + lane;
;     f32x4 v[8]; float s = 0.f;
; #pragma unroll
;     for (int j = 0; j < 8; ++j) { v[j] = __builtin_nontemporal_load(xr + 64 * j); s += (v[j].x * v[j].x + v[j].y * v[j].y) + (v[j].z * v[j].z + v[j].w * v[j].w); }
;     const float rs = rsqrtf(wave_sum(s) * (1.f / D) + EPS);
; __device__ __forceinline__ void phase0(const Frame& F, const Args& a) {
;     ...
;     for (int m = gw; m < BATCH * NMEM; m += NGW) rms_row_bf16(a.mem + (size_t)m * D, a.norm_mem, (bf16_t*)(ws + WS_MEMN) + (size_t)m * D, F.lane);
.LBB0_42:
	global_load_dwordx4 v[34:37], v[24:25], off offset:-4096 nt
	global_load_dwordx4 v[38:41], v[24:25], off offset:-3072 nt
	global_load_dwordx4 v[42:45], v[24:25], off offset:-2048 nt
	global_load_dwordx4 v[6:9], v[24:25], off nt
	global_load_dwordx4 v[46:49], v[24:25], off offset:1024 nt
	global_load_dwordx4 v[50:53], v[24:25], off offset:-1024 nt
	global_load_dwordx4 v[2:5], v[24:25], off offset:3072 nt
	global_load_dwordx4 v[10:13], v[24:25], off offset:2048 nt
	v_mov_b32_e32 v54, v92
	v_mov_b32_e32 v55, v93
	v_mov_b32_e32 v56, v94
	v_mov_b32_e32 v57, v95
	s_add_i32 s9, s9, s94
	v_lshl_add_u64 v[24:25], v[24:25], 0, s[0:1]
	s_cmpk_gt_i32 s9, 0x3ff
	s_waitcnt vmcnt(7)
	v_mov_b32_e32 v60, v35
	s_waitcnt vmcnt(6)
	v_mov_b32_e32 v61, v39
	v_mov_b32_e32 v64, v37
	v_mov_b32_e32 v65, v41
	v_mov_b32_e32 v58, v34
	v_mov_b32_e32 v59, v38
	v_mov_b32_e32 v62, v36
	v_mov_b32_e32 v63, v40
	s_waitcnt vmcnt(5)
	v_pk_mul_f32 v[66:67], v[44:45], v[44:45]
	v_pk_mul_f32 v[68:69], v[42:43], v[42:43]
	v_pk_mul_f32 v[60:61], v[60:61], v[60:61]
	v_pk_mul_f32 v[64:65], v[64:65], v[64:65]
	v_pk_mov_b32 v[82:83], v[68:69], v[66:67] op_sel:[1,0]
	v_mov_b32_e32 v69, v67
	v_pk_fma_f32 v[58:59], v[58:59], v[58:59], v[60:61]
	v_pk_fma_f32 v[60:61], v[62:63], v[62:63], v[64:65]
	s_waitcnt vmcnt(3)
	v_pk_mul_f32 v[70:71], v[48:49], v[48:49]
	v_pk_mul_f32 v[72:73], v[46:47], v[46:47]
	s_waitcnt vmcnt(2)
	v_mul_f32_e32 v74, v51, v51
	v_mul_f32_e32 v76, v53, v53
	v_pk_add_f32 v[62:63], v[82:83], v[68:69]
	v_pk_add_f32 v[58:59], v[58:59], v[60:61]
	v_mul_f32_e32 v81, v6, v6
	v_mul_f32_e32 v84, v7, v7
	v_mul_f32_e32 v85, v8, v8
	v_mul_f32_e32 v86, v9, v9
	v_pk_mov_b32 v[66:67], v[72:73], v[70:71] op_sel:[1,0]
	v_mov_b32_e32 v73, v71
	v_pk_fma_f32 v[70:71], v[50:51], v[50:51], v[74:75] op_sel_hi:[1,1,0]
	v_pk_fma_f32 v[74:75], v[52:53], v[52:53], v[76:77] op_sel_hi:[1,1,0]
	v_pk_add_f32 v[60:61], v[62:63], v[62:63] op_sel:[0,1] op_sel_hi:[1,0]
	v_pk_add_f32 v[58:59], v[58:59], v[58:59] op_sel:[0,1] op_sel_hi:[1,0]
	v_mov_b32_e32 v71, v85
	v_mov_b32_e32 v75, v86
	v_mov_b32_e32 v61, v84
	v_mov_b32_e32 v59, v81
	v_pk_add_f32 v[62:63], v[70:71], v[74:75]
	v_pk_add_f32 v[58:59], v[58:59], v[60:61]
	s_waitcnt vmcnt(0)
	v_mul_f32_e32 v78, v11, v11
	v_mul_f32_e32 v80, v13, v13
	v_pk_add_f32 v[64:65], v[66:67], v[72:73]
	v_pk_add_f32 v[58:59], v[58:59], v[62:63]
	v_mul_f32_e32 v87, v2, v2
	v_mul_f32_e32 v88, v3, v3
	v_mul_f32_e32 v89, v4, v4
	v_mul_f32_e32 v90, v5, v5
	v_pk_fma_f32 v[76:77], v[10:11], v[10:11], v[78:79] op_sel_hi:[1,1,0]
	v_pk_fma_f32 v[78:79], v[12:13], v[12:13], v[80:81] op_sel_hi:[1,1,0]
	v_pk_add_f32 v[64:65], v[64:65], v[64:65] op_sel:[0,1] op_sel_hi:[1,0]
	v_pk_add_f32 v[58:59], v[58:59], v[58:59] op_sel:[0,1] op_sel_hi:[1,0]
	v_mov_b32_e32 v77, v89
	v_mov_b32_e32 v79, v90
	v_mov_b32_e32 v65, v88
	v_mov_b32_e32 v59, v87
	v_pk_add_f32 v[66:67], v[76:77], v[78:79]
	v_pk_add_f32 v[58:59], v[58:59], v[64:65]
	s_nop 0
	v_pk_add_f32 v[58:59], v[58:59], v[66:67]
	s_nop 0
	v_add_f32_e32 v58, v58, v59
	ds_bpermute_b32 v59, v1, v58
	s_waitcnt lgkmcnt(0)
	v_add_f32_e32 v58, v58, v59
	ds_bpermute_b32 v59, v28, v58
	s_waitcnt lgkmcnt(0)
	v_add_f32_e32 v58, v58, v59
	ds_bpermute_b32 v59, v29, v58
	s_waitcnt lgkmcnt(0)
	v_add_f32_e32 v58, v58, v59
	ds_bpermute_b32 v59, v30, v58
	s_waitcnt lgkmcnt(0)
	v_add_f32_e32 v58, v58, v59
	ds_bpermute_b32 v59, v31, v58
	s_waitcnt lgkmcnt(0)
	v_add_f32_e32 v58, v58, v59
	ds_bpermute_b32 v59, v32, v58
	s_waitcnt lgkmcnt(0)
; __device__ __forceinline__ unsigned cvt_pk_bf16(float lo, float hi) { unsigned r; asm volatile("v_cvt_pk_bf16_f32 %0, %1, %2" : "=v"(r) : "v"(lo), "v"(hi)); return r; }
; __device__ __forceinline__ void rms_row_bf16(const float* xrow, const float* gain, bf16_t* orow, int lane) {
;     ...
;     const float rs = rsqrtf(wave_sum(s) * (1.f / D) + EPS);
;     u32x2* o8 = (u32x2*)orow + lane;
; #pragma unroll
;     for (int j = 0; j < 8; ++j) { const f32x4 g = gr[64 * j]; u32x2 w; w.x = cvt_pk_bf16(v[j].x * rs * g.x, v[j].y * rs * g.y); w.y = cvt_pk_bf16(v[j].z * rs * g.z, v[j].w * rs * g.w); o8[64 * j] = w; }
; }
	v_add_f32_e32 v58, v58, v59
	v_fmamk_f32 v58, v58, 0x3a000000, v33
	v_mul_f32_e32 v59, 0x4b800000, v58
	v_cmp_gt_f32_e32 vcc, s8, v58
	s_nop 1
	v_cndmask_b32_e32 v58, v58, v59, vcc
	v_rsq_f32_e32 v58, v58
	s_nop 0
	v_mul_f32_e32 v59, 0x45800000, v58
	v_cndmask_b32_e32 v58, v58, v59, vcc
	v_mul_f32_e32 v34, v34, v58
	v_mul_f32_e32 v35, v35, v58
	v_mul_f32_e32 v36, v36, v58
	v_mul_f32_e32 v37, v37, v58
	s_waitcnt vmcnt(0)
	v_mul_f32_e32 v34, v54, v34
	v_mul_f32_e32 v35, v55, v35
	v_mul_f32_e32 v36, v56, v36
	v_mul_f32_e32 v37, v57, v37
	v_cvt_pk_bf16_f32 v34, v34, v35
	v_cvt_pk_bf16_f32 v35, v36, v37
	global_store_dwordx2 v[26:27], v[34:35], off
	v_mov_b32_e32 v34, v96
	v_mov_b32_e32 v35, v97
	v_mov_b32_e32 v36, v98
	v_mov_b32_e32 v37, v99
	v_mul_f32_e32 v38, v38, v58
	v_mul_f32_e32 v39, v39, v58
	v_mul_f32_e32 v40, v40, v58
	v_mul_f32_e32 v41, v41, v58
	v_mul_f32_e32 v6, v6, v58
	v_mul_f32_e32 v7, v7, v58
	v_mul_f32_e32 v8, v8, v58
	v_mul_f32_e32 v9, v9, v58
	v_mul_f32_e32 v10, v10, v58
	v_mul_f32_e32 v11, v11, v58
	v_mul_f32_e32 v12, v12, v58
	v_mul_f32_e32 v13, v13, v58
	v_mul_f32_e32 v2, v2, v58
	v_mul_f32_e32 v3, v3, v58
	v_mul_f32_e32 v4, v4, v58
	v_mul_f32_e32 v5, v5, v58
	v_mul_f32_e32 v34, v34, v38
	v_mul_f32_e32 v35, v35, v39
	v_mul_f32_e32 v36, v36, v40
	v_mul_f32_e32 v37, v37, v41
	v_cvt_pk_bf16_f32 v34, v34, v35
	v_cvt_pk_bf16_f32 v35, v36, v37
	global_store_dwordx2 v[26:27], v[34:35], off offset:512
	v_mov_b32_e32 v34, v100
	v_mov_b32_e32 v35, v101
	v_mov_b32_e32 v36, v102
	v_mov_b32_e32 v37, v103
	v_mul_f32_e32 v38, v42, v58
	v_mul_f32_e32 v39, v43, v58
	v_mul_f32_e32 v40, v44, v58
	v_mul_f32_e32 v41, v45, v58
	v_mul_f32_e32 v34, v34, v38
	v_mul_f32_e32 v35, v35, v39
	v_mul_f32_e32 v36, v36, v40
	v_mul_f32_e32 v37, v37, v41
	v_cvt_pk_bf16_f32 v34, v34, v35
	v_cvt_pk_bf16_f32 v35, v36, v37
	global_store_dwordx2 v[26:27], v[34:35], off offset:1024
	v_mov_b32_e32 v34, v104
	v_mov_b32_e32 v35, v105
	v_mov_b32_e32 v36, v106
	v_mov_b32_e32 v37, v107
	v_mul_f32_e32 v38, v50, v58
	v_mul_f32_e32 v39, v51, v58
	v_mul_f32_e32 v40, v52, v58
	v_mul_f32_e32 v41, v53, v58
	v_mul_f32_e32 v34, v38, v34
	v_mul_f32_e32 v35, v39, v35
	v_mul_f32_e32 v36, v40, v36
	v_mul_f32_e32 v37, v41, v37
	v_cvt_pk_bf16_f32 v34, v34, v35
	v_cvt_pk_bf16_f32 v35, v36, v37
	global_store_dwordx2 v[26:27], v[34:35], off offset:1536
	v_mov_b32_e32 v34, v108
	v_mov_b32_e32 v35, v109
	v_mov_b32_e32 v36, v110
	v_mov_b32_e32 v37, v111
	v_mul_f32_e32 v6, v6, v34
	v_mul_f32_e32 v7, v7, v35
	v_mul_f32_e32 v8, v8, v36
	v_mul_f32_e32 v9, v9, v37
	v_cvt_pk_bf16_f32 v6, v6, v7
	v_cvt_pk_bf16_f32 v7, v8, v9
	global_store_dwordx2 v[26:27], v[6:7], off offset:2048
	v_mov_b32_e32 v6, v112
	v_mov_b32_e32 v7, v113
	v_mov_b32_e32 v8, v114
	v_mov_b32_e32 v9, v115
	v_mul_f32_e32 v34, v46, v58
	v_mul_f32_e32 v35, v47, v58
	v_mul_f32_e32 v36, v48, v58
	v_mul_f32_e32 v37, v49, v58
	v_mul_f32_e32 v6, v34, v6
	v_mul_f32_e32 v7, v35, v7
	v_mul_f32_e32 v8, v36, v8
	v_mul_f32_e32 v9, v37, v9
	v_cvt_pk_bf16_f32 v6, v6, v7
	v_cvt_pk_bf16_f32 v7, v8, v9
	global_store_dwordx2 v[26:27], v[6:7], off offset:2560
	v_mov_b32_e32 v6, v116
	v_mov_b32_e32 v7, v117
	v_mov_b32_e32 v8, v118
	v_mov_b32_e32 v9, v119
	v_mul_f32_e32 v6, v10, v6
	v_mul_f32_e32 v7, v11, v7
	v_mul_f32_e32 v8, v12, v8
	v_mul_f32_e32 v9, v13, v9
	v_cvt_pk_bf16_f32 v6, v6, v7
	v_cvt_pk_bf16_f32 v7, v8, v9
	global_store_dwordx2 v[26:27], v[6:7], off offset:3072
	v_mov_b32_e32 v6, v120
	v_mov_b32_e32 v7, v121
	v_mov_b32_e32 v8, v122
	v_mov_b32_e32 v9, v123
	v_mul_f32_e32 v2, v2, v6
	v_mul_f32_e32 v3, v3, v7
	v_mul_f32_e32 v4, v4, v8
	v_mul_f32_e32 v5, v5, v9
	v_cvt_pk_bf16_f32 v2, v2, v3
	v_cvt_pk_bf16_f32 v3, v4, v5
	global_store_dwordx2 v[26:27], v[2:3], off offset:3584
	v_lshl_add_u64 v[26:27], v[26:27], 0, s[2:3]
	s_cbranch_scc0 .LBB0_42

; __device__ __forceinline__ float bflo(unsigned w) { return __uint_as_float(w << 16); }
; __device__ __forceinline__ float bfhi(unsigned w) { return __uint_as_float(w & 0xffff0000u); }
; __device__ __forceinline__ void rms_row_add_bf16(const float* xrow, const bf16_t* mrow, const float* gain, bf16_t* orow, int lane) {
;     const f32x4* xr = (const f32x4*)xrow + lane; const u32x2* mr = (const u32x2*)mrow + lane; const f32x4* gr = (const f32x4*)gain + lane;
;     f32x4 v[8]; float s = 0.f;
; #pragma unroll
;     for (int j = 0; j < 8; ++j) { const u32x2 mm = mr[64 * j]; v[j] = __builtin_nontemporal_load(xr + 64 * j); v[j].x += bflo(mm.x); v[j].y += bfhi(mm.x); v[j].z += bflo(mm.y); v[j].w += bfhi(mm.y);
;         s += (v[j].x * v[j].x + v[j].y * v[j].y) + (v[j].z * v[j].z + v[j].w * v[j].w); }
; __global__ void __launch_bounds__(512, 2) mega_fwd(Args a) {
;     ...
;     if (IN(7)) { for (int m = gw; m < M; m += NGW) rms_row_add_bf16(a.x + (size_t)m * D, (const bf16_t*)(ws + WS_H2) + (size_t)m * D, a.norm_mlp, (bf16_t*)(ws + WS_H) + (size_t)m * D, F.lane); }
.LBB0_1064:
	s_cmp_lt_i32 s24, 8
	s_cselect_b64 s[2:3], -1, 0
	s_and_b64 s[0:1], s[2:3], s[0:1]
	s_cmpk_lt_i32 s92, 0x4000
	s_cselect_b64 s[4:5], -1, 0
	s_and_b64 s[2:3], s[0:1], s[4:5]
	s_andn2_b64 vcc, exec, s[2:3]
	v_lshlrev_b32_e32 v128, 4, v192
	v_mbcnt_lo_u32_b32 v145, -1, 0
	v_lshlrev_b32_e32 v130, 3, v192
	s_cbranch_vccnz .LBB0_1067
	v_mbcnt_hi_u32_b32 v2, -1, v145
	v_and_b32_e32 v3, 64, v2
	v_add_u32_e32 v3, 64, v3
	v_xor_b32_e32 v4, 1, v2
	v_cmp_lt_i32_e32 vcc, v4, v3
	v_readlane_b32 s36, v242, 1
	v_mov_b32_e32 v129, 0
	v_cndmask_b32_e32 v4, v2, v4, vcc
	v_lshlrev_b32_e32 v14, 2, v4
	v_xor_b32_e32 v4, 2, v2
	v_cmp_lt_i32_e32 vcc, v4, v3
	v_readlane_b32 s46, v242, 11
	v_readlane_b32 s47, v242, 12
	v_cndmask_b32_e32 v4, v2, v4, vcc
	v_lshlrev_b32_e32 v15, 2, v4
	v_xor_b32_e32 v4, 4, v2
	v_cmp_lt_i32_e32 vcc, v4, v3
	v_lshl_add_u64 v[0:1], s[46:47], 0, v[128:129]
	s_mov_b64 s[2:3], 0x1400
	v_cndmask_b32_e32 v4, v2, v4, vcc
	v_lshlrev_b32_e32 v16, 2, v4
	v_xor_b32_e32 v4, 8, v2
	v_cmp_lt_i32_e32 vcc, v4, v3
	s_ashr_i32 s93, s92, 31
	v_mov_b32_e32 v131, v129
	v_cndmask_b32_e32 v4, v2, v4, vcc
	v_lshlrev_b32_e32 v17, 2, v4
	v_xor_b32_e32 v4, 16, v2
	v_cmp_lt_i32_e32 vcc, v4, v3
	v_readlane_b32 s37, v242, 2
	s_mov_b64 s[6:7], 0x1000
	v_cndmask_b32_e32 v4, v2, v4, vcc
	v_lshlrev_b32_e32 v18, 2, v4
	v_xor_b32_e32 v4, 32, v2
	v_cmp_lt_i32_e32 vcc, v4, v3
	v_mov_b32_e32 v20, 0x358637bd
	s_mov_b32 s10, s92
	v_cndmask_b32_e32 v2, v2, v4, vcc
	v_lshl_add_u64 v[4:5], v[0:1], 0, s[2:3]
	s_mov_b64 s[2:3], 0x1800
	v_lshl_add_u64 v[6:7], v[0:1], 0, s[2:3]
	s_mov_b64 s[2:3], 0x1c00
	v_lshl_add_u64 v[8:9], v[0:1], 0, s[2:3]
	s_lshl_b64 s[2:3], s[92:93], 12
	s_add_u32 s2, s22, s2
	s_addc_u32 s3, s23, s3
	v_lshl_add_u64 v[10:11], s[2:3], 0, v[130:131]
	s_mov_b64 s[2:3], 0xa400000
	s_ashr_i32 s95, s94, 31
	v_lshl_add_u64 v[10:11], v[10:11], 0, s[2:3]
	s_lshl_b64 s[2:3], s[94:95], 12
	s_lshl_b64 s[8:9], s[92:93], 13
	s_add_u32 s8, s36, s8
	s_addc_u32 s9, s37, s9
	v_lshl_add_u64 v[12:13], s[8:9], 0, v[128:129]
	v_lshlrev_b32_e32 v19, 2, v2
	v_lshl_add_u64 v[2:3], v[0:1], 0, s[6:7]
	v_lshl_add_u64 v[12:13], v[12:13], 0, s[6:7]
	s_lshl_b64 s[6:7], s[94:95], 13
	s_mov_b32 s8, 0xf6a01000
	s_mov_b32 s9, 0x800000
	v_readlane_b32 s38, v242, 3
	v_readlane_b32 s39, v242, 4
	v_readlane_b32 s40, v242, 5
	v_readlane_b32 s41, v242, 6
	v_readlane_b32 s42, v242, 7
	v_readlane_b32 s43, v242, 8
	v_readlane_b32 s44, v242, 9
	v_readlane_b32 s45, v242, 10
	v_readlane_b32 s48, v242, 13
	v_readlane_b32 s49, v242, 14
	v_readlane_b32 s50, v242, 15
	v_readlane_b32 s51, v242, 16
	global_load_dwordx4 v[84:87], v[0:1], off
	global_load_dwordx4 v[88:91], v[0:1], off offset:1024
	global_load_dwordx4 v[92:95], v[0:1], off offset:2048
	global_load_dwordx4 v[96:99], v[0:1], off offset:3072
	global_load_dwordx4 v[100:103], v[2:3], off
	global_load_dwordx4 v[104:107], v[4:5], off
	global_load_dwordx4 v[108:111], v[6:7], off
	global_load_dwordx4 v[112:115], v[8:9], off
	s_waitcnt vmcnt(0)
.LBB0_1066:
	v_add_co_u32_e32 v30, vcc, 0xf6a00000, v10
	global_load_dwordx4 v[22:25], v[12:13], off offset:-1024 nt
	s_nop 0
	v_addc_co_u32_e32 v31, vcc, -1, v11, vcc
	global_load_dwordx2 v[54:55], v[30:31], off
	global_load_dwordx4 v[26:29], v[12:13], off offset:-4096 nt
	v_add_co_u32_e32 v56, vcc, s8, v10
	s_add_i32 s10, s10, s94
	s_nop 0
	v_addc_co_u32_e32 v57, vcc, -1, v11, vcc
	global_load_dwordx2 v[58:59], v[56:57], off offset:-3584
	global_load_dwordx2 v[60:61], v[56:57], off offset:-3072
	global_load_dwordx2 v[62:63], v[56:57], off offset:-2560
	global_load_dwordx2 v[64:65], v[56:57], off offset:-2048
	global_load_dwordx2 v[66:67], v[56:57], off offset:-1536
	global_load_dwordx4 v[30:33], v[12:13], off offset:-3072 nt
	global_load_dwordx4 v[34:37], v[12:13], off offset:-2048 nt
	global_load_dwordx4 v[38:41], v[12:13], off nt
	global_load_dwordx4 v[42:45], v[12:13], off offset:1024 nt
	global_load_dwordx2 v[68:69], v[56:57], off offset:-1024
	global_load_dwordx4 v[46:49], v[12:13], off offset:2048 nt
	global_load_dwordx4 v[50:53], v[12:13], off offset:3072 nt
	global_load_dwordx2 v[70:71], v[56:57], off offset:-512
	s_cmpk_lt_i32 s10, 0x4000
	v_lshl_add_u64 v[12:13], v[12:13], 0, s[6:7]
	s_waitcnt vmcnt(0)
	v_lshlrev_b32_e32 v73, 16, v60
	v_and_b32_e32 v75, 0xffff0000, v60
	v_mov_b32_e32 v56, v22
	v_mov_b32_e32 v57, v24
	v_lshlrev_b32_e32 v21, 16, v54
	v_mov_b32_e32 v24, v23
	v_and_b32_e32 v54, 0xffff0000, v54
	v_lshlrev_b32_e32 v22, 16, v55
	v_and_b32_e32 v23, 0xffff0000, v55
	v_add_f32_e32 v21, v26, v21
	v_add_f32_e32 v74, v27, v54
	v_pk_add_f32 v[26:27], v[28:29], v[22:23]
	v_lshlrev_b32_e32 v22, 16, v58
	v_and_b32_e32 v23, 0xffff0000, v58
	v_lshlrev_b32_e32 v28, 16, v59
	v_and_b32_e32 v29, 0xffff0000, v59
	v_lshlrev_b32_e32 v76, 16, v61
	v_and_b32_e32 v77, 0xffff0000, v61
	v_lshlrev_b32_e32 v55, 16, v63
	v_lshlrev_b32_e32 v54, 16, v62
	v_and_b32_e32 v59, 0xffff0000, v63
	v_and_b32_e32 v58, 0xffff0000, v62
	v_lshlrev_b32_e32 v60, 16, v64
	v_and_b32_e32 v61, 0xffff0000, v64
	v_lshlrev_b32_e32 v62, 16, v65
	v_and_b32_e32 v63, 0xffff0000, v65
	v_mul_f32_e32 v64, v21, v21
	v_add_f32_e32 v65, v34, v73
	v_pk_add_f32 v[30:31], v[30:31], v[22:23]
	v_pk_add_f32 v[28:29], v[32:33], v[28:29]
	v_add_f32_e32 v75, v35, v75
	v_mul_f32_e32 v22, v27, v27
	v_pk_add_f32 v[34:35], v[24:25], v[58:59]
	v_pk_mul_f32 v[24:25], v[64:65], v[64:65]
	v_mul_f32_e32 v72, v74, v74
	v_add_f32_e32 v76, v36, v76
	v_add_f32_e32 v77, v37, v77
	v_pk_add_f32 v[36:37], v[38:39], v[60:61]
	v_pk_add_f32 v[38:39], v[40:41], v[62:63]
	v_mul_f32_e32 v41, v75, v75
	v_mov_b32_e32 v73, v65
	v_pk_fma_f32 v[22:23], v[26:27], v[26:27], v[22:23] op_sel_hi:[1,1,0]
; __device__ __forceinline__ float bflo(unsigned w) { return __uint_as_float(w << 16); }
; __device__ __forceinline__ float bfhi(unsigned w) { return __uint_as_float(w & 0xffff0000u); }
; __device__ __forceinline__ void rms_row_add_bf16(const float* xrow, const bf16_t* mrow, const float* gain, bf16_t* orow, int lane) {
;     ...
;     for (int j = 0; j < 8; ++j) { const u32x2 mm = mr[64 * j]; v[j] = __builtin_nontemporal_load(xr + 64 * j); v[j].x += bflo(mm.x); v[j].y += bfhi(mm.x); v[j].z += bflo(mm.y); v[j].w += bfhi(mm.y);
;         s += (v[j].x * v[j].x + v[j].y * v[j].y) + (v[j].z * v[j].z + v[j].w * v[j].w); }
;     const float rs = rsqrtf(wave_sum(s) * (1.f / D) + EPS);
;     u32x2* o8 = (u32x2*)orow + lane;
	v_mul_f32_e32 v24, v31, v31
	v_mul_f32_e32 v40, v29, v29
	v_mul_f32_e32 v79, v76, v76
	v_mul_f32_e32 v80, v77, v77
	v_pk_add_f32 v[60:61], v[64:65], v[72:73]
	v_mov_b32_e32 v23, v41
	v_pk_fma_f32 v[62:63], v[30:31], v[30:31], v[24:25] op_sel_hi:[1,1,0]
	v_pk_fma_f32 v[40:41], v[28:29], v[28:29], v[40:41] op_sel_hi:[1,1,0]
	v_mov_b32_e32 v61, v25
	v_mov_b32_e32 v63, v79
	v_mov_b32_e32 v41, v80
	v_pk_add_f32 v[22:23], v[60:61], v[22:23]
	v_pk_add_f32 v[24:25], v[62:63], v[40:41]
	v_lshlrev_b32_e32 v78, 16, v66
	v_pk_add_f32 v[22:23], v[22:23], v[24:25]
	v_pk_add_f32 v[32:33], v[56:57], v[54:55]
	v_pk_add_f32 v[40:41], v[22:23], v[22:23] op_sel:[0,1] op_sel_hi:[1,0]
	v_and_b32_e32 v22, 0xffff0000, v66
	v_add_f32_e32 v66, v43, v22
	v_lshlrev_b32_e32 v22, 16, v67
	v_add_f32_e32 v72, v44, v22
	v_and_b32_e32 v22, 0xffff0000, v67
	v_add_f32_e32 v67, v45, v22
	v_lshlrev_b32_e32 v22, 16, v68
	v_and_b32_e32 v23, 0xffff0000, v68
	v_pk_add_f32 v[46:47], v[46:47], v[22:23]
	v_lshlrev_b32_e32 v22, 16, v69
	v_and_b32_e32 v23, 0xffff0000, v69
	v_pk_add_f32 v[48:49], v[48:49], v[22:23]
	v_mov_b32_e32 v22, v84
	v_mov_b32_e32 v23, v85
	v_mov_b32_e32 v24, v86
	v_mov_b32_e32 v25, v87
	v_pk_mul_f32 v[54:55], v[34:35], v[34:35]
	v_mul_f32_e32 v58, v39, v39
	v_lshlrev_b32_e32 v41, 16, v71
	v_mul_f32_e32 v56, v37, v37
	v_pk_fma_f32 v[54:55], v[32:33], v[32:33], v[54:55]
	v_pk_fma_f32 v[58:59], v[38:39], v[38:39], v[58:59] op_sel_hi:[1,1,0]
	v_add_f32_e32 v68, v52, v41
	v_and_b32_e32 v41, 0xffff0000, v71
	v_pk_fma_f32 v[56:57], v[36:37], v[36:37], v[56:57] op_sel_hi:[1,1,0]
	v_lshlrev_b32_e32 v59, 16, v70
	v_add_f32_e32 v69, v53, v41
	v_pk_add_f32 v[52:53], v[54:55], v[54:55] op_sel:[0,1] op_sel_hi:[1,0]
	v_add_f32_e32 v64, v42, v78
	v_and_b32_e32 v45, 0xffff0000, v70
	v_mov_b32_e32 v41, v50
	v_mov_b32_e32 v53, v59
	v_mov_b32_e32 v57, v50
	v_mul_f32_e32 v42, v64, v64
	v_mul_f32_e32 v44, v66, v66
	v_mul_f32_e32 v60, v72, v72
	v_mul_f32_e32 v62, v67, v67
	v_pk_add_f32 v[40:41], v[40:41], v[52:53]
	v_pk_add_f32 v[52:53], v[56:57], v[58:59]
	v_mov_b32_e32 v43, v51
	v_mov_b32_e32 v61, v51
	v_mov_b32_e32 v63, v45
	v_pk_add_f32 v[42:43], v[42:43], v[44:45]
	v_pk_add_f32 v[44:45], v[60:61], v[62:63]
	v_pk_add_f32 v[50:51], v[40:41], v[52:53]
	v_pk_mul_f32 v[52:53], v[40:41], v[52:53]
	v_mul_f32_e32 v40, v47, v47
	v_mov_b32_e32 v51, v53
	v_pk_add_f32 v[52:53], v[42:43], v[44:45]
	v_pk_mul_f32 v[44:45], v[42:43], v[44:45]
	v_mul_f32_e32 v70, v68, v68
	v_mov_b32_e32 v53, v45
	v_pk_add_f32 v[44:45], v[50:51], v[52:53]
	v_pk_fma_f32 v[50:51], v[46:47], v[46:47], v[40:41] op_sel_hi:[1,1,0]
	v_mul_f32_e32 v40, v49, v49
	v_mul_f32_e32 v71, v69, v69
	v_pk_fma_f32 v[52:53], v[48:49], v[48:49], v[40:41] op_sel_hi:[1,1,0]
	v_mov_b32_e32 v51, v70
	v_mov_b32_e32 v53, v71
	v_pk_add_f32 v[50:51], v[50:51], v[52:53]
	s_nop 0
	v_pk_add_f32 v[44:45], v[44:45], v[50:51]
	s_nop 0
	v_add_f32_e32 v40, v44, v45
	ds_bpermute_b32 v42, v14, v40
	s_waitcnt lgkmcnt(0)
	v_add_f32_e32 v40, v40, v42
	ds_bpermute_b32 v42, v15, v40
	s_waitcnt lgkmcnt(0)
	v_add_f32_e32 v40, v40, v42
	ds_bpermute_b32 v42, v16, v40
	s_waitcnt lgkmcnt(0)
	v_add_f32_e32 v40, v40, v42
	ds_bpermute_b32 v42, v17, v40
	s_waitcnt lgkmcnt(0)
	v_add_f32_e32 v40, v40, v42
	ds_bpermute_b32 v42, v18, v40
	s_waitcnt lgkmcnt(0)
	v_add_f32_e32 v40, v40, v42
	ds_bpermute_b32 v42, v19, v40
	s_waitcnt lgkmcnt(0)
; __device__ __forceinline__ unsigned cvt_pk_bf16(float lo, float hi) { unsigned r; asm volatile("v_cvt_pk_bf16_f32 %0, %1, %2" : "=v"(r) : "v"(lo), "v"(hi)); return r; }
; __device__ __forceinline__ void rms_row_add_bf16(const float* xrow, const bf16_t* mrow, const float* gain, bf16_t* orow, int lane) {
;     ...
;     const float rs = rsqrtf(wave_sum(s) * (1.f / D) + EPS);
;     u32x2* o8 = (u32x2*)orow + lane;
; #pragma unroll
;     for (int j = 0; j < 8; ++j) { const f32x4 g = gr[64 * j]; u32x2 w; w.x = cvt_pk_bf16(v[j].x * rs * g.x, v[j].y * rs * g.y); w.y = cvt_pk_bf16(v[j].z * rs * g.z, v[j].w * rs * g.w); o8[64 * j] = w; }
	v_add_f32_e32 v40, v40, v42
	v_fmamk_f32 v40, v40, 0x3a000000, v20
	v_mul_f32_e32 v42, 0x4b800000, v40
	v_cmp_gt_f32_e32 vcc, s9, v40
	s_nop 1
	v_cndmask_b32_e32 v40, v40, v42, vcc
	v_rsq_f32_e32 v40, v40
	s_nop 0
	v_mul_f32_e32 v42, 0x45800000, v40
	v_cndmask_b32_e32 v40, v40, v42, vcc
	v_mul_f32_e32 v21, v21, v40
	v_mul_f32_e32 v21, v22, v21
	v_mul_f32_e32 v22, v74, v40
	v_mul_f32_e32 v22, v23, v22
	v_mul_f32_e32 v23, v27, v40
	v_cvt_pk_bf16_f32 v22, v21, v22
	v_mul_f32_e32 v21, v26, v40
	v_mul_f32_e32 v23, v25, v23
	v_mul_f32_e32 v21, v24, v21
	v_cvt_pk_bf16_f32 v23, v21, v23
	global_store_dwordx2 v[10:11], v[22:23], off
	v_mov_b32_e32 v22, v88
	v_mov_b32_e32 v23, v89
	v_mov_b32_e32 v24, v90
	v_mov_b32_e32 v25, v91
	v_mul_f32_e32 v21, v30, v40
	v_mul_f32_e32 v26, v31, v40
	v_mul_f32_e32 v27, v28, v40
	v_mul_f32_e32 v28, v29, v40
	v_mul_f32_e32 v21, v22, v21
	v_mul_f32_e32 v22, v23, v26
	v_mul_f32_e32 v23, v24, v27
	v_mul_f32_e32 v24, v25, v28
	v_cvt_pk_bf16_f32 v22, v21, v22
	v_cvt_pk_bf16_f32 v23, v23, v24
	global_store_dwordx2 v[10:11], v[22:23], off offset:512
	v_mov_b32_e32 v22, v92
	v_mov_b32_e32 v23, v93
	v_mov_b32_e32 v24, v94
	v_mov_b32_e32 v25, v95
	v_mul_f32_e32 v21, v65, v40
	v_mul_f32_e32 v26, v75, v40
	v_mul_f32_e32 v27, v76, v40
	v_mul_f32_e32 v28, v77, v40
	v_mul_f32_e32 v21, v22, v21
	v_mul_f32_e32 v22, v23, v26
	v_mul_f32_e32 v23, v24, v27
	v_mul_f32_e32 v24, v25, v28
	v_cvt_pk_bf16_f32 v22, v21, v22
	v_cvt_pk_bf16_f32 v23, v23, v24
	global_store_dwordx2 v[10:11], v[22:23], off offset:1024
	v_mov_b32_e32 v22, v96
	v_mov_b32_e32 v23, v97
	v_mov_b32_e32 v24, v98
	v_mov_b32_e32 v25, v99
	v_mul_f32_e32 v21, v32, v40
	v_mul_f32_e32 v26, v34, v40
	v_mul_f32_e32 v27, v33, v40
	v_mul_f32_e32 v28, v35, v40
	v_mul_f32_e32 v21, v21, v22
	v_mul_f32_e32 v22, v26, v23
	v_mul_f32_e32 v23, v27, v24
	v_mul_f32_e32 v24, v28, v25
	v_cvt_pk_bf16_f32 v22, v21, v22
	v_cvt_pk_bf16_f32 v23, v23, v24
	global_store_dwordx2 v[10:11], v[22:23], off offset:1536
	v_mov_b32_e32 v22, v100
	v_mov_b32_e32 v23, v101
	v_mov_b32_e32 v24, v102
	v_mov_b32_e32 v25, v103
	v_mul_f32_e32 v21, v36, v40
	v_mul_f32_e32 v26, v37, v40
	v_mul_f32_e32 v27, v38, v40
	v_mul_f32_e32 v28, v39, v40
	v_mul_f32_e32 v21, v21, v22
	v_mul_f32_e32 v22, v26, v23
	v_mul_f32_e32 v23, v27, v24
	v_mul_f32_e32 v24, v28, v25
	v_cvt_pk_bf16_f32 v22, v21, v22
	v_cvt_pk_bf16_f32 v23, v23, v24
	global_store_dwordx2 v[10:11], v[22:23], off offset:2048
	v_mov_b32_e32 v22, v104
	v_mov_b32_e32 v23, v105
	v_mov_b32_e32 v24, v106
	v_mov_b32_e32 v25, v107
	v_mul_f32_e32 v21, v64, v40
	v_mul_f32_e32 v26, v66, v40
	v_mul_f32_e32 v27, v72, v40
	v_mul_f32_e32 v28, v67, v40
	v_mul_f32_e32 v21, v21, v22
	v_mul_f32_e32 v22, v26, v23
	v_mul_f32_e32 v23, v27, v24
	v_mul_f32_e32 v24, v28, v25
	v_cvt_pk_bf16_f32 v22, v21, v22
	v_cvt_pk_bf16_f32 v23, v23, v24
	global_store_dwordx2 v[10:11], v[22:23], off offset:2560
	v_mov_b32_e32 v22, v108
	v_mov_b32_e32 v23, v109
	v_mov_b32_e32 v24, v110
	v_mov_b32_e32 v25, v111
	v_mul_f32_e32 v21, v46, v40
	v_mul_f32_e32 v26, v47, v40
	v_mul_f32_e32 v27, v48, v40
	v_mul_f32_e32 v28, v49, v40
	v_mul_f32_e32 v21, v21, v22
	v_mul_f32_e32 v22, v26, v23
	v_mul_f32_e32 v23, v27, v24
	v_mul_f32_e32 v24, v28, v25
	v_cvt_pk_bf16_f32 v22, v21, v22
	v_cvt_pk_bf16_f32 v23, v23, v24
	global_store_dwordx2 v[10:11], v[22:23], off offset:3072
	v_mov_b32_e32 v22, v112
	v_mov_b32_e32 v23, v113
	v_mov_b32_e32 v24, v114
	v_mov_b32_e32 v25, v115
	v_mul_f32_e32 v21, v41, v40
	v_mul_f32_e32 v26, v43, v40
	v_mul_f32_e32 v27, v68, v40
	v_mul_f32_e32 v28, v69, v40
	v_mul_f32_e32 v21, v21, v22
	v_mul_f32_e32 v22, v26, v23
	v_mul_f32_e32 v23, v27, v24
	v_mul_f32_e32 v24, v28, v25
	v_cvt_pk_bf16_f32 v22, v21, v22
	v_cvt_pk_bf16_f32 v23, v23, v24
	global_store_dwordx2 v[10:11], v[22:23], off offset:3584
	v_lshl_add_u64 v[10:11], v[10:11], 0, s[2:3]
	s_cbranch_scc1 .LBB0_1066

; __device__ __forceinline__ void rms_row_final(const float* xrow, const bf16_t* mrow, const bf16_t* drow, const float* gain, float* orow, int lane) {
;     const f32x4* xr = (const f32x4*)xrow + lane; const u32x2* mr = (const u32x2*)mrow + lane; const u32x2* dr = (const u32x2*)drow + lane; const f32x4* gr = (const f32x4*)gain + lane;
;     f32x4 v[8]; float s = 0.f;
; #pragma unroll
;     for (int j = 0; j < 8; ++j) { const u32x2 mm = mr[64 * j], dd = dr[64 * j]; v[j] = __builtin_nontemporal_load(xr + 64 * j);
; __global__ void __launch_bounds__(512, 2) mega_fwd(Args a) {
;     ...
;     if (IN(10)) { for (int m = gw; m < M; m += NGW) rms_row_final(a.x + (size_t)m * D, (const bf16_t*)(ws + WS_H2) + (size_t)m * D, (const bf16_t*)(ws + WS_H) + (size_t)m * D, a.norm_final, a.out + (size_t)m * D, F.lane); }
.LBB0_1220:
	s_cmp_lt_i32 s24, 11
	s_cselect_b64 s[2:3], -1, 0
	s_and_b64 s[0:1], s[2:3], s[0:1]
	s_and_b64 s[0:1], s[0:1], s[4:5]
	s_andn2_b64 vcc, exec, s[0:1]
	s_cbranch_vccnz .LBB0_1223
	v_mbcnt_hi_u32_b32 v2, -1, v145
	v_and_b32_e32 v3, 64, v2
	v_add_u32_e32 v3, 64, v3
	v_xor_b32_e32 v4, 1, v2
	v_cmp_lt_i32_e32 vcc, v4, v3
	v_readlane_b32 s4, v242, 1
	v_mov_b32_e32 v129, 0
	v_cndmask_b32_e32 v4, v2, v4, vcc
	v_lshlrev_b32_e32 v20, 2, v4
	v_xor_b32_e32 v4, 2, v2
	v_cmp_lt_i32_e32 vcc, v4, v3
	v_readlane_b32 s16, v242, 13
	v_readlane_b32 s17, v242, 14
	v_cndmask_b32_e32 v4, v2, v4, vcc
	v_lshlrev_b32_e32 v21, 2, v4
	v_xor_b32_e32 v4, 4, v2
	v_cmp_lt_i32_e32 vcc, v4, v3
	v_lshl_add_u64 v[0:1], s[16:17], 0, v[128:129]
	s_mov_b64 s[0:1], 0x1000
	v_cndmask_b32_e32 v4, v2, v4, vcc
	v_lshlrev_b32_e32 v22, 2, v4
	v_xor_b32_e32 v4, 8, v2
	v_cmp_lt_i32_e32 vcc, v4, v3
	s_ashr_i32 s93, s92, 31
	v_mov_b32_e32 v131, v129
	v_cndmask_b32_e32 v4, v2, v4, vcc
	v_lshlrev_b32_e32 v23, 2, v4
	v_xor_b32_e32 v4, 16, v2
	v_cmp_lt_i32_e32 vcc, v4, v3
	v_readlane_b32 s5, v242, 2
	v_readlane_b32 s6, v242, 3
	v_cndmask_b32_e32 v4, v2, v4, vcc
	v_lshlrev_b32_e32 v24, 2, v4
	v_xor_b32_e32 v4, 32, v2
	v_cmp_lt_i32_e32 vcc, v4, v3
	v_readlane_b32 s7, v242, 4
	v_readlane_b32 s8, v242, 5
	v_cndmask_b32_e32 v2, v2, v4, vcc
	v_lshlrev_b32_e32 v25, 2, v2
	v_lshl_add_u64 v[2:3], v[0:1], 0, s[0:1]
	s_mov_b64 s[0:1], 0x1400
	v_lshl_add_u64 v[4:5], v[0:1], 0, s[0:1]
	s_mov_b64 s[0:1], 0x1800
	v_lshl_add_u64 v[6:7], v[0:1], 0, s[0:1]
	s_mov_b64 s[0:1], 0x1c00
	v_lshl_add_u64 v[8:9], v[0:1], 0, s[0:1]
	s_lshl_b64 s[0:1], s[92:93], 12
	s_add_u32 s0, s22, s0
	s_addc_u32 s1, s23, s1
	v_lshl_add_u64 v[10:11], s[0:1], 0, v[130:131]
	s_mov_b64 s[0:1], 0xa400000
	s_ashr_i32 s95, s94, 31
	v_lshl_add_u64 v[10:11], v[10:11], 0, s[0:1]
	s_lshl_b64 s[2:3], s[94:95], 12
	s_lshl_b64 s[0:1], s[92:93], 13
	s_add_u32 s4, s4, s0
	s_addc_u32 s5, s5, s1
	s_lshl_b64 s[6:7], s[94:95], 13
	v_readlane_b32 s9, v242, 6
	v_readlane_b32 s10, v242, 7
	v_readlane_b32 s11, v242, 8
	v_readlane_b32 s12, v242, 9
	s_add_u32 s8, s20, s0
	s_addc_u32 s9, s21, s1
	s_mov_b32 s10, 0xf6a01000
	s_movk_i32 s11, 0x1000
	v_mov_b32_e32 v26, 0x358637bd
	s_mov_b32 s12, 0x800000
	v_readlane_b32 s13, v242, 10
	v_readlane_b32 s14, v242, 11
	v_readlane_b32 s15, v242, 12
	v_readlane_b32 s18, v242, 15
	v_readlane_b32 s19, v242, 16
	global_load_dwordx4 v[146:149], v[0:1], off
	global_load_dwordx4 v[150:153], v[0:1], off offset:1024
	global_load_dwordx4 v[154:157], v[0:1], off offset:2048
	global_load_dwordx4 v[158:161], v[0:1], off offset:3072
	global_load_dwordx4 v[162:165], v[2:3], off
	global_load_dwordx4 v[166:169], v[4:5], off
	global_load_dwordx4 v[170:173], v[6:7], off
	global_load_dwordx4 v[174:177], v[8:9], off
	s_waitcnt vmcnt(0)
.LBB0_1222:
	v_add_co_u32_e64 v76, s[0:1], s10, v10
	global_load_dwordx2 v[12:13], v[10:11], off
	global_load_dwordx2 v[14:15], v[10:11], off offset:512
	global_load_dwordx2 v[16:17], v[10:11], off offset:1024
	global_load_dwordx2 v[64:65], v[10:11], off offset:1536
	global_load_dwordx2 v[66:67], v[10:11], off offset:2048
	global_load_dwordx2 v[68:69], v[10:11], off offset:2560
	v_lshl_add_u64 v[48:49], s[4:5], 0, v[128:129]
	v_add_co_u32_e32 v70, vcc, 0xf6a00000, v10
	global_load_dwordx2 v[72:73], v[10:11], off offset:3072
	global_load_dwordx2 v[74:75], v[10:11], off offset:3584
	v_addc_co_u32_e64 v77, s[0:1], -1, v11, s[0:1]
	v_mov_b32_e32 v28, v146
	v_mov_b32_e32 v29, v147
	v_mov_b32_e32 v30, v148
	v_mov_b32_e32 v31, v149
	global_load_dwordx2 v[78:79], v[76:77], off offset:-2048
	global_load_dwordx2 v[80:81], v[76:77], off offset:-1536
	v_addc_co_u32_e32 v71, vcc, -1, v11, vcc
	global_load_dwordx4 v[32:35], v[48:49], off nt
	global_load_dwordx4 v[36:39], v[48:49], off offset:1024 nt
	global_load_dwordx2 v[82:83], v[76:77], off offset:-1024
	global_load_dwordx4 v[40:43], v[48:49], off offset:2048 nt
	global_load_dwordx4 v[44:47], v[48:49], off offset:3072 nt
	global_load_dwordx2 v[84:85], v[76:77], off offset:-512
	v_add_co_u32_e32 v86, vcc, s11, v48
	v_lshl_add_u64 v[18:19], s[8:9], 0, v[128:129]
	s_nop 0
	v_addc_co_u32_e32 v87, vcc, 0, v49, vcc
	global_load_dwordx2 v[88:89], v[70:71], off
	global_load_dwordx2 v[90:91], v[76:77], off offset:-3584
	global_load_dwordx2 v[92:93], v[76:77], off offset:-3072
	global_load_dwordx2 v[94:95], v[76:77], off offset:-2560
	global_load_dwordx4 v[48:51], v[86:87], off nt
	global_load_dwordx4 v[52:55], v[86:87], off offset:1024 nt
	global_load_dwordx4 v[56:59], v[86:87], off offset:2048 nt
	global_load_dwordx4 v[60:63], v[86:87], off offset:3072 nt
	s_add_i32 s92, s92, s94
	s_add_u32 s4, s4, s6
	s_addc_u32 s5, s5, s7
	s_add_u32 s8, s8, s6
	s_addc_u32 s9, s9, s7
	v_lshl_add_u64 v[10:11], v[10:11], 0, s[2:3]
	s_cmpk_lt_i32 s92, 0x4000
	s_waitcnt vmcnt(0)
; __device__ __forceinline__ float bflo(unsigned w) { return __uint_as_float(w << 16); }
; __device__ __forceinline__ float bfhi(unsigned w) { return __uint_as_float(w & 0xffff0000u); }
; __device__ __forceinline__ void rms_row_final(const float* xrow, const bf16_t* mrow, const bf16_t* drow, const float* gain, float* orow, int lane) {
;     ...
;     for (int j = 0; j < 8; ++j) { const u32x2 mm = mr[64 * j], dd = dr[64 * j]; v[j] = __builtin_nontemporal_load(xr + 64 * j);
;         v[j].x += bflo(mm.x) + bflo(dd.x); v[j].y += bfhi(mm.x) + bfhi(dd.x); v[j].z += bflo(mm.y) + bflo(dd.y); v[j].w += bfhi(mm.y) + bfhi(dd.y);
;         s += (v[j].x * v[j].x + v[j].y * v[j].y) + (v[j].z * v[j].z + v[j].w * v[j].w); }
	v_lshlrev_b32_e32 v70, 16, v12
	v_and_b32_e32 v71, 0xffff0000, v12
	v_lshlrev_b32_e32 v12, 16, v13
	v_and_b32_e32 v13, 0xffff0000, v13
	v_lshlrev_b32_e32 v76, 16, v14
	v_and_b32_e32 v77, 0xffff0000, v14
	v_lshlrev_b32_e32 v14, 16, v15
	v_and_b32_e32 v15, 0xffff0000, v15
	v_lshlrev_b32_e32 v98, 16, v66
	v_and_b32_e32 v99, 0xffff0000, v66
	v_lshlrev_b32_e32 v66, 16, v67
	v_and_b32_e32 v67, 0xffff0000, v67
	v_lshlrev_b32_e32 v100, 16, v68
	v_and_b32_e32 v101, 0xffff0000, v68
	v_lshlrev_b32_e32 v68, 16, v69
	v_and_b32_e32 v69, 0xffff0000, v69
	v_lshlrev_b32_e32 v102, 16, v72
	v_and_b32_e32 v103, 0xffff0000, v72
	v_lshlrev_b32_e32 v72, 16, v73
	v_and_b32_e32 v73, 0xffff0000, v73
	v_lshlrev_b32_e32 v106, 16, v78
	v_and_b32_e32 v107, 0xffff0000, v78
	v_lshlrev_b32_e32 v78, 16, v79
	v_and_b32_e32 v79, 0xffff0000, v79
	v_lshlrev_b32_e32 v108, 16, v80
	v_and_b32_e32 v109, 0xffff0000, v80
	v_lshlrev_b32_e32 v80, 16, v81
	v_and_b32_e32 v81, 0xffff0000, v81
	v_lshlrev_b32_e32 v110, 16, v82
	v_and_b32_e32 v111, 0xffff0000, v82
	v_lshlrev_b32_e32 v82, 16, v83
	v_and_b32_e32 v83, 0xffff0000, v83
	v_lshlrev_b32_e32 v114, 16, v88
	v_and_b32_e32 v115, 0xffff0000, v88
	v_lshlrev_b32_e32 v88, 16, v89
	v_and_b32_e32 v89, 0xffff0000, v89
	v_lshlrev_b32_e32 v116, 16, v90
	v_and_b32_e32 v117, 0xffff0000, v90
	v_lshlrev_b32_e32 v90, 16, v91
	v_and_b32_e32 v91, 0xffff0000, v91
	v_lshlrev_b32_e32 v86, 16, v16
	v_and_b32_e32 v87, 0xffff0000, v16
	v_lshlrev_b32_e32 v16, 16, v17
	v_and_b32_e32 v17, 0xffff0000, v17
	v_lshlrev_b32_e32 v96, 16, v64
	v_and_b32_e32 v97, 0xffff0000, v64
	v_lshlrev_b32_e32 v64, 16, v65
	v_and_b32_e32 v65, 0xffff0000, v65
	v_lshlrev_b32_e32 v104, 16, v74
	v_and_b32_e32 v105, 0xffff0000, v74
	v_lshlrev_b32_e32 v74, 16, v75
	v_and_b32_e32 v75, 0xffff0000, v75
	v_lshlrev_b32_e32 v112, 16, v84
	v_and_b32_e32 v113, 0xffff0000, v84
	v_lshlrev_b32_e32 v84, 16, v85
	v_and_b32_e32 v85, 0xffff0000, v85
	v_lshlrev_b32_e32 v118, 16, v92
	v_and_b32_e32 v119, 0xffff0000, v92
	v_lshlrev_b32_e32 v92, 16, v93
	v_and_b32_e32 v93, 0xffff0000, v93
	v_lshlrev_b32_e32 v120, 16, v94
	v_and_b32_e32 v121, 0xffff0000, v94
	v_lshlrev_b32_e32 v94, 16, v95
	v_and_b32_e32 v95, 0xffff0000, v95
	v_pk_add_f32 v[66:67], v[78:79], v[66:67]
	v_pk_add_f32 v[78:79], v[108:109], v[100:101]
	v_pk_add_f32 v[68:69], v[80:81], v[68:69]
	v_pk_add_f32 v[80:81], v[110:111], v[102:103]
	v_pk_add_f32 v[72:73], v[82:83], v[72:73]
	v_pk_add_f32 v[70:71], v[114:115], v[70:71]
	v_pk_add_f32 v[12:13], v[88:89], v[12:13]
	v_pk_add_f32 v[76:77], v[116:117], v[76:77]
	v_pk_add_f32 v[14:15], v[90:91], v[14:15]
	v_pk_add_f32 v[74:75], v[84:85], v[74:75]
	v_pk_add_f32 v[84:85], v[118:119], v[86:87]
	v_pk_add_f32 v[16:17], v[92:93], v[16:17]
	v_pk_add_f32 v[64:65], v[94:95], v[64:65]
	v_pk_add_f32 v[52:53], v[52:53], v[78:79]
	v_pk_add_f32 v[54:55], v[54:55], v[68:69]
	v_pk_add_f32 v[56:57], v[56:57], v[80:81]
	v_pk_add_f32 v[58:59], v[58:59], v[72:73]
	v_pk_add_f32 v[32:33], v[32:33], v[70:71]
	v_pk_add_f32 v[12:13], v[34:35], v[12:13]
	v_pk_add_f32 v[34:35], v[36:37], v[76:77]
	v_pk_add_f32 v[36:37], v[38:39], v[14:15]
	v_pk_add_f32 v[86:87], v[120:121], v[96:97]
	v_pk_add_f32 v[50:51], v[50:51], v[66:67]
	v_pk_add_f32 v[62:63], v[62:63], v[74:75]
	v_pk_add_f32 v[38:39], v[40:41], v[84:85]
	v_pk_add_f32 v[16:17], v[42:43], v[16:17]
	v_pk_add_f32 v[42:43], v[46:47], v[64:65]
	v_mov_b32_e32 v64, v53
	v_mov_b32_e32 v65, v55
	v_mul_f32_e32 v66, v57, v57
	v_mul_f32_e32 v68, v59, v59
	v_mov_b32_e32 v76, v33
	v_mov_b32_e32 v77, v35
	v_mov_b32_e32 v80, v13
	v_mov_b32_e32 v81, v37
	v_pk_add_f32 v[82:83], v[112:113], v[104:105]
	v_pk_add_f32 v[40:41], v[44:45], v[86:87]
	v_mov_b32_e32 v46, v52
	v_mov_b32_e32 v47, v54
	v_pk_mul_f32 v[72:73], v[62:63], v[62:63]
	v_mov_b32_e32 v74, v32
	v_mov_b32_e32 v75, v34
	v_mov_b32_e32 v78, v12
	v_mov_b32_e32 v79, v36
	v_mov_b32_e32 v84, v39
	v_mov_b32_e32 v85, v17
	v_pk_mul_f32 v[64:65], v[64:65], v[64:65]
	v_pk_fma_f32 v[66:67], v[56:57], v[56:57], v[66:67] op_sel_hi:[1,1,0]
	v_pk_fma_f32 v[68:69], v[58:59], v[58:59], v[68:69] op_sel_hi:[1,1,0]
	v_pk_mul_f32 v[76:77], v[76:77], v[76:77]
	v_pk_mul_f32 v[80:81], v[80:81], v[80:81]
	v_pk_add_f32 v[98:99], v[106:107], v[98:99]
	v_pk_add_f32 v[60:61], v[60:61], v[82:83]
	v_mov_b32_e32 v82, v38
	v_mov_b32_e32 v83, v16
	v_mul_f32_e32 v86, v41, v41
	v_mul_f32_e32 v88, v43, v43
	v_pk_mul_f32 v[84:85], v[84:85], v[84:85]
	v_pk_fma_f32 v[46:47], v[46:47], v[46:47], v[64:65]
	v_mov_b32_e32 v67, v72
	v_mov_b32_e32 v69, v73
	v_pk_fma_f32 v[64:65], v[74:75], v[74:75], v[76:77]
	v_pk_fma_f32 v[72:73], v[78:79], v[78:79], v[80:81]
	v_pk_add_f32 v[48:49], v[48:49], v[98:99]
	v_pk_mul_f32 v[44:45], v[50:51], v[50:51]
	v_pk_fma_f32 v[86:87], v[40:41], v[40:41], v[86:87] op_sel_hi:[1,1,0]
	v_pk_fma_f32 v[88:89], v[42:43], v[42:43], v[88:89] op_sel_hi:[1,1,0]
	v_pk_fma_f32 v[74:75], v[82:83], v[82:83], v[84:85]
	v_pk_add_f32 v[64:65], v[64:65], v[72:73]
	v_pk_mul_f32 v[14:15], v[48:49], v[48:49]
	v_mov_b32_e32 v87, v44
	v_mov_b32_e32 v89, v45
	v_pk_add_f32 v[44:45], v[46:47], v[46:47] op_sel:[0,1] op_sel_hi:[1,0]
	v_pk_add_f32 v[46:47], v[66:67], v[68:69]
	v_pk_add_f32 v[66:67], v[74:75], v[74:75] op_sel:[0,1] op_sel_hi:[1,0]
	v_pk_add_f32 v[64:65], v[64:65], v[64:65] op_sel:[0,1] op_sel_hi:[1,0]
	v_mov_b32_e32 v67, v15
	v_mov_b32_e32 v65, v14
	v_pk_add_f32 v[68:69], v[86:87], v[88:89]
	v_pk_add_f32 v[14:15], v[64:65], v[66:67]
	v_pk_mul_f32 v[70:71], v[60:61], v[60:61]
	v_pk_add_f32 v[14:15], v[14:15], v[68:69]
	v_mov_b32_e32 v45, v71
	v_pk_add_f32 v[14:15], v[14:15], v[14:15] op_sel:[0,1] op_sel_hi:[1,0]
	s_nop 0
	v_mov_b32_e32 v15, v70
	v_pk_add_f32 v[14:15], v[14:15], v[44:45]
	s_nop 0
	v_pk_add_f32 v[14:15], v[14:15], v[46:47]
	s_nop 0
	v_add_f32_e32 v14, v14, v15
	ds_bpermute_b32 v15, v20, v14
	s_waitcnt lgkmcnt(0)
; __device__ __forceinline__ void rms_row_final(const float* xrow, const bf16_t* mrow, const bf16_t* drow, const float* gain, float* orow, int lane) {
;     ...
;     const float rs = rsqrtf(wave_sum(s) * (1.f / D) + EPS);
;     f32x4* o = (f32x4*)orow + lane;
; #pragma unroll
;     for (int j = 0; j < 8; ++j) { const f32x4 g = gr[64 * j]; o[64 * j] = v[j] * rs * g; }
	v_add_f32_e32 v14, v14, v15
	ds_bpermute_b32 v15, v21, v14
	s_waitcnt lgkmcnt(0)
	v_add_f32_e32 v14, v14, v15
	ds_bpermute_b32 v15, v22, v14
	s_waitcnt lgkmcnt(0)
	v_add_f32_e32 v14, v14, v15
	ds_bpermute_b32 v15, v23, v14
	s_waitcnt lgkmcnt(0)
	v_add_f32_e32 v14, v14, v15
	ds_bpermute_b32 v15, v24, v14
	s_waitcnt lgkmcnt(0)
	v_add_f32_e32 v14, v14, v15
	ds_bpermute_b32 v15, v25, v14
	s_waitcnt lgkmcnt(0)
	v_add_f32_e32 v14, v14, v15
	v_fmamk_f32 v14, v14, 0x3a000000, v26
	v_mul_f32_e32 v15, 0x4b800000, v14
	v_cmp_gt_f32_e32 vcc, s12, v14
	s_nop 1
	v_cndmask_b32_e32 v14, v14, v15, vcc
	v_rsq_f32_e32 v14, v14
	s_nop 0
	v_mul_f32_e32 v15, 0x45800000, v14
	v_cndmask_b32_e32 v44, v14, v15, vcc
	v_pk_mul_f32 v[32:33], v[32:33], v[44:45] op_sel_hi:[1,0]
	v_pk_mul_f32 v[12:13], v[12:13], v[44:45] op_sel_hi:[1,0]
	v_pk_mul_f32 v[16:17], v[16:17], v[44:45] op_sel_hi:[1,0]
	v_pk_mul_f32 v[14:15], v[30:31], v[12:13]
	v_pk_mul_f32 v[12:13], v[28:29], v[32:33]
	global_store_dwordx4 v[18:19], v[12:15], off
	s_nop 1
	v_mov_b32_e32 v12, v150
	v_mov_b32_e32 v13, v151
	v_mov_b32_e32 v14, v152
	v_mov_b32_e32 v15, v153
	v_pk_mul_f32 v[28:29], v[36:37], v[44:45] op_sel_hi:[1,0]
	v_pk_mul_f32 v[30:31], v[34:35], v[44:45] op_sel_hi:[1,0]
	v_pk_mul_f32 v[14:15], v[14:15], v[28:29]
	v_pk_mul_f32 v[12:13], v[12:13], v[30:31]
	global_store_dwordx4 v[18:19], v[12:15], off offset:1024
	s_nop 1
	v_mov_b32_e32 v12, v154
	v_mov_b32_e32 v13, v155
	v_mov_b32_e32 v14, v156
	v_mov_b32_e32 v15, v157
	v_pk_mul_f32 v[28:29], v[38:39], v[44:45] op_sel_hi:[1,0]
	v_pk_mul_f32 v[14:15], v[14:15], v[16:17]
	v_pk_mul_f32 v[12:13], v[12:13], v[28:29]
	global_store_dwordx4 v[18:19], v[12:15], off offset:2048
	s_nop 1
	v_mov_b32_e32 v12, v158
	v_mov_b32_e32 v13, v159
	v_mov_b32_e32 v14, v160
	v_mov_b32_e32 v15, v161
	v_pk_mul_f32 v[16:17], v[42:43], v[44:45] op_sel_hi:[1,0]
	v_pk_mul_f32 v[28:29], v[40:41], v[44:45] op_sel_hi:[1,0]
	v_pk_mul_f32 v[14:15], v[14:15], v[16:17]
	v_pk_mul_f32 v[12:13], v[12:13], v[28:29]
	global_store_dwordx4 v[18:19], v[12:15], off offset:3072
	s_nop 1
	v_mov_b32_e32 v12, v162
	v_mov_b32_e32 v13, v163
	v_mov_b32_e32 v14, v164
	v_mov_b32_e32 v15, v165
	v_add_co_u32_e32 v16, vcc, s11, v18
	v_pk_mul_f32 v[28:29], v[48:49], v[44:45] op_sel_hi:[1,0]
	s_nop 0
	v_addc_co_u32_e32 v17, vcc, 0, v19, vcc
	v_pk_mul_f32 v[18:19], v[50:51], v[44:45] op_sel_hi:[1,0]
	v_pk_mul_f32 v[12:13], v[12:13], v[28:29]
	v_pk_mul_f32 v[14:15], v[14:15], v[18:19]
	global_store_dwordx4 v[16:17], v[12:15], off
	s_nop 1
	v_mov_b32_e32 v12, v166
	v_mov_b32_e32 v13, v167
	v_mov_b32_e32 v14, v168
	v_mov_b32_e32 v15, v169
	v_pk_mul_f32 v[18:19], v[54:55], v[44:45] op_sel_hi:[1,0]
	v_pk_mul_f32 v[28:29], v[52:53], v[44:45] op_sel_hi:[1,0]
	v_pk_mul_f32 v[14:15], v[14:15], v[18:19]
	v_pk_mul_f32 v[12:13], v[12:13], v[28:29]
	global_store_dwordx4 v[16:17], v[12:15], off offset:1024
	s_nop 1
	v_mov_b32_e32 v12, v170
	v_mov_b32_e32 v13, v171
	v_mov_b32_e32 v14, v172
	v_mov_b32_e32 v15, v173
	v_pk_mul_f32 v[18:19], v[58:59], v[44:45] op_sel_hi:[1,0]
	v_pk_mul_f32 v[28:29], v[56:57], v[44:45] op_sel_hi:[1,0]
	v_pk_mul_f32 v[14:15], v[14:15], v[18:19]
	v_pk_mul_f32 v[12:13], v[12:13], v[28:29]
	global_store_dwordx4 v[16:17], v[12:15], off offset:2048
	s_nop 1
	v_mov_b32_e32 v12, v174
	v_mov_b32_e32 v13, v175
	v_mov_b32_e32 v14, v176
	v_mov_b32_e32 v15, v177
	v_pk_mul_f32 v[18:19], v[62:63], v[44:45] op_sel_hi:[1,0]
	v_pk_mul_f32 v[28:29], v[60:61], v[44:45] op_sel_hi:[1,0]
	v_pk_mul_f32 v[14:15], v[14:15], v[18:19]
	v_pk_mul_f32 v[12:13], v[12:13], v[28:29]
	global_store_dwordx4 v[16:17], v[12:15], off offset:3072
	s_cbranch_scc1 .LBB0_1222
